# first K-iteration DMA wait of GEMM units relaxed past the epilogue stores (vmcnt 24/63 at four sites), on top of the rope-lookup hoist
# baseline (speedup 1.0000x reference)
.LBB0_344:
	s_ashr_i32 s13, s12, 31
	s_lshl_b64 s[14:15], s[12:13], 18
	s_add_u32 s14, s17, s14
	s_addc_u32 s15, s18, s15
	s_and_b64 s[20:21], s[4:5], exec
	s_cselect_b32 s13, s15, s25
	s_cselect_b32 s40, s14, s24
	s_ashr_i32 s11, s10, 31
	s_lshl_b64 s[20:21], s[10:11], 18
	s_add_u32 s20, s19, s20
	s_addc_u32 s21, s28, s21
	s_and_b64 s[30:31], s[4:5], exec
	s_cselect_b32 s11, s21, s27
	s_cselect_b32 s41, s20, s26
	s_add_u32 s24, s24, 0x20080
	s_addc_u32 s25, s25, 0
	s_add_u32 s43, s26, 0x100
	s_addc_u32 s44, s27, 0
	s_mov_b32 s45, -2
	v_add_u32_e32 v253, 0x10000, v154
	s_add_u32 s26, s24, 0xfffe0080
	s_addc_u32 s27, s25, -1
	s_add_i32 s46, 0, 0x10000
	s_cmp_eq_u32 s45, 4
	s_cselect_b32 s31, s13, s27
	s_cselect_b32 s30, s40, s26
	s_cselect_b32 s27, s11, s44
	s_cselect_b32 s26, s41, s43
	s_add_i32 s52, 0, 0x14000
	ds_read_b128 v[158:161], v253
	ds_read_b128 v[162:165], v253 offset:1024
	ds_read_b128 v[166:169], v253 offset:2048
	ds_read_b128 v[170:173], v253 offset:3072
	ds_read_b128 v[174:177], v253 offset:16384
	ds_read_b128 v[178:181], v253 offset:17408
	ds_read_b128 v[182:185], v253 offset:18432
	ds_read_b128 v[186:189], v253 offset:19456
	s_add_i32 m0, s23, 0xc000
	ds_read_b128 v[190:193], v156
	ds_read_b128 v[204:207], v156 offset:1024
	ds_read_b128 v[208:211], v156 offset:2048
	ds_read_b128 v[212:215], v156 offset:3072
	ds_read_b128 v[216:219], v156 offset:4096
	ds_read_b128 v[220:223], v156 offset:5120
	ds_read_b128 v[224:227], v156 offset:6144
	ds_read_b128 v[228:231], v156 offset:7168
	global_load_lds_dwordx4 v136, s[24:25]
	s_add_i32 m0, s23, 0xe000
	s_nop 0
	global_load_lds_dwordx4 v138, s[24:25]
	s_waitcnt vmcnt(24)
	s_waitcnt lgkmcnt(0)
	s_barrier
	s_setprio 1
	s_waitcnt lgkmcnt(0)
	v_mfma_f32_16x16x32_bf16 v[126:129], v[158:161], v[190:193], 0
	v_mfma_f32_16x16x32_bf16 v[122:125], v[166:169], v[190:193], 0
	v_mfma_f32_16x16x32_bf16 v[114:117], v[158:161], v[208:211], 0
	v_mfma_f32_16x16x32_bf16 v[106:109], v[166:169], v[208:211], 0
	v_mfma_f32_16x16x32_bf16 v[98:101], v[158:161], v[216:219], 0
	v_mfma_f32_16x16x32_bf16 v[90:93], v[166:169], v[216:219], 0
	v_mfma_f32_16x16x32_bf16 v[82:85], v[158:161], v[224:227], 0
	v_mfma_f32_16x16x32_bf16 v[74:77], v[166:169], v[224:227], 0
	v_mfma_f32_16x16x32_bf16 v[126:129], v[162:165], v[204:207], v[126:129]
	v_mfma_f32_16x16x32_bf16 v[122:125], v[170:173], v[204:207], v[122:125]
	v_mfma_f32_16x16x32_bf16 v[114:117], v[162:165], v[212:215], v[114:117]
	v_mfma_f32_16x16x32_bf16 v[106:109], v[170:173], v[212:215], v[106:109]
	v_mfma_f32_16x16x32_bf16 v[98:101], v[162:165], v[220:223], v[98:101]
	v_mfma_f32_16x16x32_bf16 v[90:93], v[170:173], v[220:223], v[90:93]
	v_mfma_f32_16x16x32_bf16 v[82:85], v[162:165], v[228:231], v[82:85]
	v_mfma_f32_16x16x32_bf16 v[74:77], v[170:173], v[228:231], v[74:77]
	s_setprio 0
	s_setprio 1
	v_mfma_f32_16x16x32_bf16 v[118:121], v[174:177], v[190:193], 0
	v_mfma_f32_16x16x32_bf16 v[110:113], v[182:185], v[190:193], 0
	v_mfma_f32_16x16x32_bf16 v[102:105], v[174:177], v[208:211], 0
	v_mfma_f32_16x16x32_bf16 v[94:97], v[182:185], v[208:211], 0
	v_mfma_f32_16x16x32_bf16 v[86:89], v[174:177], v[216:219], 0
	v_mfma_f32_16x16x32_bf16 v[78:81], v[182:185], v[216:219], 0
	v_mfma_f32_16x16x32_bf16 v[70:73], v[174:177], v[224:227], 0
	v_mfma_f32_16x16x32_bf16 v[66:69], v[182:185], v[224:227], 0
	v_mfma_f32_16x16x32_bf16 v[118:121], v[178:181], v[204:207], v[118:121]
	v_mfma_f32_16x16x32_bf16 v[110:113], v[186:189], v[204:207], v[110:113]
	v_mfma_f32_16x16x32_bf16 v[102:105], v[178:181], v[212:215], v[102:105]
	v_mfma_f32_16x16x32_bf16 v[94:97], v[186:189], v[212:215], v[94:97]
	v_mfma_f32_16x16x32_bf16 v[86:89], v[178:181], v[220:223], v[86:89]
	v_mfma_f32_16x16x32_bf16 v[78:81], v[186:189], v[220:223], v[78:81]
	v_mfma_f32_16x16x32_bf16 v[70:73], v[178:181], v[228:231], v[70:73]
	v_mfma_f32_16x16x32_bf16 v[66:69], v[186:189], v[228:231], v[66:69]
	s_setprio 0
	s_barrier
	s_add_i32 s46, s46, s29
	s_mov_b32 m0, s46
	ds_read_b128 v[190:193], v156 offset:16384
	ds_read_b128 v[204:207], v156 offset:17408
	ds_read_b128 v[208:211], v156 offset:18432
	ds_read_b128 v[212:215], v156 offset:19456
	ds_read_b128 v[216:219], v156 offset:20480
	ds_read_b128 v[220:223], v156 offset:21504
	ds_read_b128 v[224:227], v156 offset:22528
	ds_read_b128 v[228:231], v156 offset:23552
	global_load_lds_dwordx4 v0, s[26:27]
	s_add_i32 m0, s46, 0x2000
	s_add_u32 s50, s26, 0x20000
	s_addc_u32 s51, s27, 0
	s_add_i32 s46, s52, s29
	global_load_lds_dwordx4 v130, s[26:27]
	s_mov_b32 m0, s46
	s_nop 0
	global_load_lds_dwordx4 v0, s[50:51]
	s_add_i32 m0, s46, 0x2000
	s_nop 0
	global_load_lds_dwordx4 v130, s[50:51]
	s_mov_b32 m0, s23
	s_nop 0
	global_load_lds_dwordx4 v134, s[30:31]
	s_mov_b32 m0, s35
	s_nop 0
	global_load_lds_dwordx4 v132, s[30:31]
	s_waitcnt vmcnt(8)
	s_waitcnt lgkmcnt(0)
	s_barrier
	s_setprio 1
	s_waitcnt lgkmcnt(0)
	v_mfma_f32_16x16x32_bf16 v[62:65], v[158:161], v[190:193], 0
	v_mfma_f32_16x16x32_bf16 v[58:61], v[166:169], v[190:193], 0
	v_mfma_f32_16x16x32_bf16 v[50:53], v[158:161], v[208:211], 0
	v_mfma_f32_16x16x32_bf16 v[42:45], v[166:169], v[208:211], 0
	v_mfma_f32_16x16x32_bf16 v[34:37], v[158:161], v[216:219], 0
	v_mfma_f32_16x16x32_bf16 v[26:29], v[166:169], v[216:219], 0
	v_mfma_f32_16x16x32_bf16 v[18:21], v[158:161], v[224:227], 0
	v_mfma_f32_16x16x32_bf16 v[10:13], v[166:169], v[224:227], 0
	v_mfma_f32_16x16x32_bf16 v[62:65], v[162:165], v[204:207], v[62:65]
	v_mfma_f32_16x16x32_bf16 v[58:61], v[170:173], v[204:207], v[58:61]
	v_mfma_f32_16x16x32_bf16 v[50:53], v[162:165], v[212:215], v[50:53]
	v_mfma_f32_16x16x32_bf16 v[42:45], v[170:173], v[212:215], v[42:45]
	v_mfma_f32_16x16x32_bf16 v[34:37], v[162:165], v[220:223], v[34:37]
	v_mfma_f32_16x16x32_bf16 v[26:29], v[170:173], v[220:223], v[26:29]
	v_mfma_f32_16x16x32_bf16 v[18:21], v[162:165], v[228:231], v[18:21]
	v_mfma_f32_16x16x32_bf16 v[10:13], v[170:173], v[228:231], v[10:13]
	s_setprio 0
	s_setprio 1
	v_mfma_f32_16x16x32_bf16 v[54:57], v[174:177], v[190:193], 0
	v_mfma_f32_16x16x32_bf16 v[46:49], v[182:185], v[190:193], 0
	v_mfma_f32_16x16x32_bf16 v[38:41], v[174:177], v[208:211], 0
	v_mfma_f32_16x16x32_bf16 v[30:33], v[182:185], v[208:211], 0
	v_mfma_f32_16x16x32_bf16 v[22:25], v[174:177], v[216:219], 0
	v_mfma_f32_16x16x32_bf16 v[14:17], v[182:185], v[216:219], 0
	v_mfma_f32_16x16x32_bf16 v[6:9], v[174:177], v[224:227], 0
	v_mfma_f32_16x16x32_bf16 v[2:5], v[182:185], v[224:227], 0
	v_mfma_f32_16x16x32_bf16 v[54:57], v[178:181], v[204:207], v[54:57]
	v_mfma_f32_16x16x32_bf16 v[46:49], v[186:189], v[204:207], v[46:49]
	v_mfma_f32_16x16x32_bf16 v[38:41], v[178:181], v[212:215], v[38:41]
	v_mfma_f32_16x16x32_bf16 v[30:33], v[186:189], v[212:215], v[30:33]
	v_mfma_f32_16x16x32_bf16 v[22:25], v[178:181], v[220:223], v[22:25]
	v_mfma_f32_16x16x32_bf16 v[14:17], v[186:189], v[220:223], v[14:17]
	v_mfma_f32_16x16x32_bf16 v[6:9], v[178:181], v[228:231], v[6:9]
	v_mfma_f32_16x16x32_bf16 v[2:5], v[186:189], v[228:231], v[2:5]
	s_setprio 0
	s_barrier
	s_add_i32 s46, 0, 0x18000
	s_add_i32 s50, 0, 0x1c000
	ds_read_b128 v[158:161], v253 offset:32768
	ds_read_b128 v[162:165], v253 offset:33792
	ds_read_b128 v[166:169], v253 offset:34816
	ds_read_b128 v[170:173], v253 offset:35840
	ds_read_b128 v[174:177], v253 offset:49152
	ds_read_b128 v[178:181], v253 offset:50176
	ds_read_b128 v[182:185], v253 offset:51200
	ds_read_b128 v[186:189], v253 offset:52224
	s_add_u32 s30, s30, 0x20000
	s_addc_u32 s31, s31, 0
	s_mov_b32 m0, s36
	ds_read_b128 v[190:193], v156 offset:32768
	ds_read_b128 v[204:207], v156 offset:33792
	ds_read_b128 v[208:211], v156 offset:34816
	ds_read_b128 v[212:215], v156 offset:35840
	ds_read_b128 v[216:219], v156 offset:36864
	ds_read_b128 v[220:223], v156 offset:37888
	ds_read_b128 v[224:227], v156 offset:38912
	ds_read_b128 v[228:231], v156 offset:39936
	global_load_lds_dwordx4 v134, s[30:31]
	s_mov_b32 m0, s37
	s_nop 0
	global_load_lds_dwordx4 v132, s[30:31]
	s_waitcnt vmcnt(8)
	s_waitcnt lgkmcnt(0)
	s_barrier
	s_setprio 1
	s_waitcnt lgkmcnt(0)
	v_mfma_f32_16x16x32_bf16 v[126:129], v[158:161], v[190:193], v[126:129]
	v_mfma_f32_16x16x32_bf16 v[122:125], v[166:169], v[190:193], v[122:125]
	v_mfma_f32_16x16x32_bf16 v[114:117], v[158:161], v[208:211], v[114:117]
	v_mfma_f32_16x16x32_bf16 v[106:109], v[166:169], v[208:211], v[106:109]
	v_mfma_f32_16x16x32_bf16 v[98:101], v[158:161], v[216:219], v[98:101]
	v_mfma_f32_16x16x32_bf16 v[90:93], v[166:169], v[216:219], v[90:93]
	v_mfma_f32_16x16x32_bf16 v[82:85], v[158:161], v[224:227], v[82:85]
	v_mfma_f32_16x16x32_bf16 v[74:77], v[166:169], v[224:227], v[74:77]
	v_mfma_f32_16x16x32_bf16 v[126:129], v[162:165], v[204:207], v[126:129]
	v_mfma_f32_16x16x32_bf16 v[122:125], v[170:173], v[204:207], v[122:125]
	v_mfma_f32_16x16x32_bf16 v[114:117], v[162:165], v[212:215], v[114:117]
	v_mfma_f32_16x16x32_bf16 v[106:109], v[170:173], v[212:215], v[106:109]
	v_mfma_f32_16x16x32_bf16 v[98:101], v[162:165], v[220:223], v[98:101]
	v_mfma_f32_16x16x32_bf16 v[90:93], v[170:173], v[220:223], v[90:93]
	v_mfma_f32_16x16x32_bf16 v[82:85], v[162:165], v[228:231], v[82:85]
	v_mfma_f32_16x16x32_bf16 v[74:77], v[170:173], v[228:231], v[74:77]
	s_setprio 0
	s_setprio 1
	v_mfma_f32_16x16x32_bf16 v[118:121], v[174:177], v[190:193], v[118:121]
	v_mfma_f32_16x16x32_bf16 v[110:113], v[182:185], v[190:193], v[110:113]
	v_mfma_f32_16x16x32_bf16 v[102:105], v[174:177], v[208:211], v[102:105]
	v_mfma_f32_16x16x32_bf16 v[94:97], v[182:185], v[208:211], v[94:97]
	v_mfma_f32_16x16x32_bf16 v[86:89], v[174:177], v[216:219], v[86:89]
	v_mfma_f32_16x16x32_bf16 v[78:81], v[182:185], v[216:219], v[78:81]
	v_mfma_f32_16x16x32_bf16 v[70:73], v[174:177], v[224:227], v[70:73]
	v_mfma_f32_16x16x32_bf16 v[66:69], v[182:185], v[224:227], v[66:69]
	v_mfma_f32_16x16x32_bf16 v[118:121], v[178:181], v[204:207], v[118:121]
	v_mfma_f32_16x16x32_bf16 v[110:113], v[186:189], v[204:207], v[110:113]
	v_mfma_f32_16x16x32_bf16 v[102:105], v[178:181], v[212:215], v[102:105]
	v_mfma_f32_16x16x32_bf16 v[94:97], v[186:189], v[212:215], v[94:97]
	v_mfma_f32_16x16x32_bf16 v[86:89], v[178:181], v[220:223], v[86:89]
	v_mfma_f32_16x16x32_bf16 v[78:81], v[186:189], v[220:223], v[78:81]
	v_mfma_f32_16x16x32_bf16 v[70:73], v[178:181], v[228:231], v[70:73]
	v_mfma_f32_16x16x32_bf16 v[66:69], v[186:189], v[228:231], v[66:69]
	s_setprio 0
	s_barrier
	s_add_u32 s100, s30, 0xfffe0080
	s_addc_u32 s101, s31, -1
	s_add_u32 s98, s26, 0x80
	s_addc_u32 s99, s27, 0
	s_add_i32 s30, s46, s29
	s_mov_b32 m0, s30
	ds_read_b128 v[190:193], v156 offset:49152
	ds_read_b128 v[204:207], v156 offset:50176
	ds_read_b128 v[208:211], v156 offset:51200
	ds_read_b128 v[212:215], v156 offset:52224
	ds_read_b128 v[216:219], v156 offset:53248
	ds_read_b128 v[220:223], v156 offset:54272
	ds_read_b128 v[224:227], v156 offset:55296
	ds_read_b128 v[228:231], v156 offset:56320
	global_load_lds_dwordx4 v0, s[98:99]
	s_add_i32 m0, s30, 0x2000
	s_add_u32 s26, s26, 0x20080
	s_addc_u32 s27, s27, 0
	s_add_i32 s30, s50, s29
	global_load_lds_dwordx4 v130, s[98:99]
	s_mov_b32 m0, s30
	s_nop 0
	global_load_lds_dwordx4 v0, s[26:27]
	s_add_i32 m0, s30, 0x2000
	s_nop 0
	global_load_lds_dwordx4 v130, s[26:27]
	s_mov_b32 m0, s38
	s_nop 0
	global_load_lds_dwordx4 v134, s[100:101]
	s_mov_b32 m0, s39
	s_nop 0
	global_load_lds_dwordx4 v132, s[100:101]
	s_waitcnt vmcnt(8)
	s_waitcnt lgkmcnt(0)
	s_barrier
	s_setprio 1
	s_waitcnt lgkmcnt(0)
	v_mfma_f32_16x16x32_bf16 v[62:65], v[158:161], v[190:193], v[62:65]
	v_mfma_f32_16x16x32_bf16 v[58:61], v[166:169], v[190:193], v[58:61]
	v_mfma_f32_16x16x32_bf16 v[50:53], v[158:161], v[208:211], v[50:53]
	v_mfma_f32_16x16x32_bf16 v[42:45], v[166:169], v[208:211], v[42:45]
	v_mfma_f32_16x16x32_bf16 v[34:37], v[158:161], v[216:219], v[34:37]
	v_mfma_f32_16x16x32_bf16 v[26:29], v[166:169], v[216:219], v[26:29]
	v_mfma_f32_16x16x32_bf16 v[18:21], v[158:161], v[224:227], v[18:21]
	v_mfma_f32_16x16x32_bf16 v[10:13], v[166:169], v[224:227], v[10:13]
	v_mfma_f32_16x16x32_bf16 v[62:65], v[162:165], v[204:207], v[62:65]
	v_mfma_f32_16x16x32_bf16 v[58:61], v[170:173], v[204:207], v[58:61]
	v_mfma_f32_16x16x32_bf16 v[50:53], v[162:165], v[212:215], v[50:53]
	v_mfma_f32_16x16x32_bf16 v[42:45], v[170:173], v[212:215], v[42:45]
	v_mfma_f32_16x16x32_bf16 v[34:37], v[162:165], v[220:223], v[34:37]
	v_mfma_f32_16x16x32_bf16 v[26:29], v[170:173], v[220:223], v[26:29]
	v_mfma_f32_16x16x32_bf16 v[18:21], v[162:165], v[228:231], v[18:21]
	v_mfma_f32_16x16x32_bf16 v[10:13], v[170:173], v[228:231], v[10:13]
	s_setprio 0
	s_setprio 1
	v_mfma_f32_16x16x32_bf16 v[54:57], v[174:177], v[190:193], v[54:57]
	v_mfma_f32_16x16x32_bf16 v[46:49], v[182:185], v[190:193], v[46:49]
	v_mfma_f32_16x16x32_bf16 v[38:41], v[174:177], v[208:211], v[38:41]
	v_mfma_f32_16x16x32_bf16 v[30:33], v[182:185], v[208:211], v[30:33]
	v_mfma_f32_16x16x32_bf16 v[22:25], v[174:177], v[216:219], v[22:25]
	v_mfma_f32_16x16x32_bf16 v[14:17], v[182:185], v[216:219], v[14:17]
	v_mfma_f32_16x16x32_bf16 v[6:9], v[174:177], v[224:227], v[6:9]
	v_mfma_f32_16x16x32_bf16 v[2:5], v[182:185], v[224:227], v[2:5]
	v_mfma_f32_16x16x32_bf16 v[54:57], v[178:181], v[204:207], v[54:57]
	v_mfma_f32_16x16x32_bf16 v[46:49], v[186:189], v[204:207], v[46:49]
	v_mfma_f32_16x16x32_bf16 v[38:41], v[178:181], v[212:215], v[38:41]
	v_mfma_f32_16x16x32_bf16 v[30:33], v[186:189], v[212:215], v[30:33]
	v_mfma_f32_16x16x32_bf16 v[22:25], v[178:181], v[220:223], v[22:25]
	v_mfma_f32_16x16x32_bf16 v[14:17], v[186:189], v[220:223], v[14:17]
	v_mfma_f32_16x16x32_bf16 v[6:9], v[178:181], v[228:231], v[6:9]
	v_mfma_f32_16x16x32_bf16 v[2:5], v[186:189], v[228:231], v[2:5]
	s_setprio 0
	s_barrier
	s_add_i32 s45, s45, 2
	s_add_u32 s24, s24, 0x100
	s_addc_u32 s25, s25, 0
	s_add_u32 s43, s43, 0x100
	s_addc_u32 s44, s44, 0
	s_cmp_gt_u32 s45, 5
	s_cbranch_scc0 .LBB0_345
	s_branch .Lpeel_exit_1

.LBB0_360:
	s_ashr_i32 s11, s10, 31
	s_lshl_b64 s[12:13], s[10:11], 17
	s_add_u32 s12, s28, s12
	s_addc_u32 s13, s29, s13
	s_and_b64 s[14:15], s[4:5], exec
	s_cselect_b32 s11, s13, s25
	s_cselect_b32 s40, s12, s24
	s_ashr_i32 s9, s8, 31
	s_lshl_b64 s[14:15], s[8:9], 17
	s_add_u32 s14, s17, s14
	s_addc_u32 s15, s18, s15
	s_and_b64 s[26:27], s[4:5], exec
	s_cselect_b32 s9, s15, s23
	s_cselect_b32 s41, s14, s22
	s_mov_b32 s36, 0
	s_mov_b64 s[26:27], -1
	s_mov_b64 s[30:31], 0
	v_add_u32_e32 v253, 0x10000, v139
	s_add_u32 s37, s24, s36
	s_addc_u32 s44, s25, 0
	s_add_u32 s42, s37, 0x100
	s_addc_u32 s43, s44, 0
	s_and_b64 s[38:39], s[30:31], exec
	s_cselect_b32 s39, s11, s43
	s_cselect_b32 s38, s40, s42
	s_add_u32 s36, s22, s36
	s_addc_u32 s42, s23, 0
	s_add_u32 s36, s36, 0x100
	s_addc_u32 s42, s42, 0
	s_add_i32 s64, 0, 0x10000
	s_and_b64 s[30:31], s[30:31], exec
	s_cselect_b32 s43, s9, s42
	s_cselect_b32 s42, s41, s36
	s_add_i32 s31, 0, 0x14000
	s_add_u32 s52, s37, 0x10080
	s_addc_u32 s53, s44, 0
	s_add_i32 s63, s64, s19
	s_add_i32 m0, s21, 0xc000
	s_add_i32 s66, s21, 0xe000
	s_add_i32 s60, s63, 0x2000
	s_add_u32 s50, s42, 0x10000
	ds_read_b128 v[144:147], v253
	ds_read_b128 v[148:151], v253 offset:1024
	ds_read_b128 v[152:155], v253 offset:2048
	ds_read_b128 v[156:159], v253 offset:3072
	s_addc_u32 s51, s43, 0
	s_add_i32 s62, s31, s19
	ds_read_b128 v[160:163], v253 offset:16384
	ds_read_b128 v[164:167], v253 offset:17408
	ds_read_b128 v[168:171], v253 offset:18432
	ds_read_b128 v[172:175], v253 offset:19456
	s_add_i32 s61, s62, 0x2000
	s_add_i32 s59, 0, 0x18000
	s_add_i32 s58, 0, 0x1c000
	s_add_u32 s36, s38, 0x10000
	s_addc_u32 s37, s39, 0
	s_add_i32 s45, s59, s19
	s_add_i32 s44, s45, 0x2000
	s_add_u32 s30, s42, 0x10080
	s_addc_u32 s31, s43, 0
	s_add_i32 s65, s58, s19
	s_add_i32 s64, s65, 0x2000
	ds_read_b128 v[176:179], v141
	ds_read_b128 v[180:183], v141 offset:1024
	ds_read_b128 v[184:187], v141 offset:2048
	ds_read_b128 v[188:191], v141 offset:3072
	ds_read_b128 v[204:207], v141 offset:4096
	ds_read_b128 v[208:211], v141 offset:5120
	ds_read_b128 v[212:215], v141 offset:6144
	ds_read_b128 v[216:219], v141 offset:7168
	global_load_lds_dwordx4 v134, s[52:53]
	s_mov_b32 m0, s66
	s_nop 0
	global_load_lds_dwordx4 v132, s[52:53]
	s_waitcnt vmcnt(24)
	s_waitcnt lgkmcnt(0)
	s_barrier
	s_setprio 1
	s_waitcnt lgkmcnt(0)
	v_mfma_f32_16x16x32_bf16 v[126:129], v[144:147], v[176:179], 0
	v_mfma_f32_16x16x32_bf16 v[122:125], v[152:155], v[176:179], 0
	v_mfma_f32_16x16x32_bf16 v[114:117], v[144:147], v[184:187], 0
	v_mfma_f32_16x16x32_bf16 v[106:109], v[152:155], v[184:187], 0
	v_mfma_f32_16x16x32_bf16 v[98:101], v[144:147], v[204:207], 0
	v_mfma_f32_16x16x32_bf16 v[90:93], v[152:155], v[204:207], 0
	v_mfma_f32_16x16x32_bf16 v[82:85], v[144:147], v[212:215], 0
	v_mfma_f32_16x16x32_bf16 v[74:77], v[152:155], v[212:215], 0
	v_mfma_f32_16x16x32_bf16 v[126:129], v[148:151], v[180:183], v[126:129]
	v_mfma_f32_16x16x32_bf16 v[122:125], v[156:159], v[180:183], v[122:125]
	v_mfma_f32_16x16x32_bf16 v[114:117], v[148:151], v[188:191], v[114:117]
	v_mfma_f32_16x16x32_bf16 v[106:109], v[156:159], v[188:191], v[106:109]
	v_mfma_f32_16x16x32_bf16 v[98:101], v[148:151], v[208:211], v[98:101]
	v_mfma_f32_16x16x32_bf16 v[90:93], v[156:159], v[208:211], v[90:93]
	v_mfma_f32_16x16x32_bf16 v[82:85], v[148:151], v[216:219], v[82:85]
	v_mfma_f32_16x16x32_bf16 v[74:77], v[156:159], v[216:219], v[74:77]
	s_setprio 0
	s_setprio 1
	v_mfma_f32_16x16x32_bf16 v[118:121], v[160:163], v[176:179], 0
	v_mfma_f32_16x16x32_bf16 v[110:113], v[168:171], v[176:179], 0
	v_mfma_f32_16x16x32_bf16 v[102:105], v[160:163], v[184:187], 0
	v_mfma_f32_16x16x32_bf16 v[94:97], v[168:171], v[184:187], 0
	v_mfma_f32_16x16x32_bf16 v[86:89], v[160:163], v[204:207], 0
	v_mfma_f32_16x16x32_bf16 v[78:81], v[168:171], v[204:207], 0
	v_mfma_f32_16x16x32_bf16 v[70:73], v[160:163], v[212:215], 0
	v_mfma_f32_16x16x32_bf16 v[66:69], v[168:171], v[212:215], 0
	v_mfma_f32_16x16x32_bf16 v[118:121], v[164:167], v[180:183], v[118:121]
	v_mfma_f32_16x16x32_bf16 v[110:113], v[172:175], v[180:183], v[110:113]
	v_mfma_f32_16x16x32_bf16 v[102:105], v[164:167], v[188:191], v[102:105]
	v_mfma_f32_16x16x32_bf16 v[94:97], v[172:175], v[188:191], v[94:97]
	v_mfma_f32_16x16x32_bf16 v[86:89], v[164:167], v[208:211], v[86:89]
	v_mfma_f32_16x16x32_bf16 v[78:81], v[172:175], v[208:211], v[78:81]
	v_mfma_f32_16x16x32_bf16 v[70:73], v[164:167], v[216:219], v[70:73]
	v_mfma_f32_16x16x32_bf16 v[66:69], v[172:175], v[216:219], v[66:69]
	s_setprio 0
	s_barrier
	s_mov_b32 m0, s63
	ds_read_b128 v[176:179], v141 offset:16384
	ds_read_b128 v[180:183], v141 offset:17408
	ds_read_b128 v[184:187], v141 offset:18432
	ds_read_b128 v[188:191], v141 offset:19456
	ds_read_b128 v[204:207], v141 offset:20480
	ds_read_b128 v[208:211], v141 offset:21504
	ds_read_b128 v[212:215], v141 offset:22528
	ds_read_b128 v[216:219], v141 offset:23552
	global_load_lds_dwordx4 v0, s[42:43]
	s_mov_b32 m0, s60
	s_nop 0
	global_load_lds_dwordx4 v130, s[42:43]
	s_mov_b32 m0, s62
	s_nop 0
	global_load_lds_dwordx4 v0, s[50:51]
	s_mov_b32 m0, s61
	s_nop 0
	global_load_lds_dwordx4 v130, s[50:51]
	s_mov_b32 m0, s21
	s_nop 0
	global_load_lds_dwordx4 v134, s[38:39]
	s_mov_b32 m0, s35
	s_nop 0
	global_load_lds_dwordx4 v132, s[38:39]
	s_waitcnt vmcnt(8)
	s_waitcnt lgkmcnt(0)
	s_barrier
	s_setprio 1
	s_waitcnt lgkmcnt(0)
	v_mfma_f32_16x16x32_bf16 v[62:65], v[144:147], v[176:179], 0
	v_mfma_f32_16x16x32_bf16 v[58:61], v[152:155], v[176:179], 0
	v_mfma_f32_16x16x32_bf16 v[50:53], v[144:147], v[184:187], 0
	v_mfma_f32_16x16x32_bf16 v[42:45], v[152:155], v[184:187], 0
	v_mfma_f32_16x16x32_bf16 v[34:37], v[144:147], v[204:207], 0
	v_mfma_f32_16x16x32_bf16 v[26:29], v[152:155], v[204:207], 0
	v_mfma_f32_16x16x32_bf16 v[18:21], v[144:147], v[212:215], 0
	v_mfma_f32_16x16x32_bf16 v[10:13], v[152:155], v[212:215], 0
	v_mfma_f32_16x16x32_bf16 v[62:65], v[148:151], v[180:183], v[62:65]
	v_mfma_f32_16x16x32_bf16 v[58:61], v[156:159], v[180:183], v[58:61]
	v_mfma_f32_16x16x32_bf16 v[50:53], v[148:151], v[188:191], v[50:53]
	v_mfma_f32_16x16x32_bf16 v[42:45], v[156:159], v[188:191], v[42:45]
	v_mfma_f32_16x16x32_bf16 v[34:37], v[148:151], v[208:211], v[34:37]
	v_mfma_f32_16x16x32_bf16 v[26:29], v[156:159], v[208:211], v[26:29]
	v_mfma_f32_16x16x32_bf16 v[18:21], v[148:151], v[216:219], v[18:21]
	v_mfma_f32_16x16x32_bf16 v[10:13], v[156:159], v[216:219], v[10:13]
	s_setprio 0
	s_setprio 1
	v_mfma_f32_16x16x32_bf16 v[54:57], v[160:163], v[176:179], 0
	v_mfma_f32_16x16x32_bf16 v[46:49], v[168:171], v[176:179], 0
	v_mfma_f32_16x16x32_bf16 v[38:41], v[160:163], v[184:187], 0
	v_mfma_f32_16x16x32_bf16 v[30:33], v[168:171], v[184:187], 0
	v_mfma_f32_16x16x32_bf16 v[22:25], v[160:163], v[204:207], 0
	v_mfma_f32_16x16x32_bf16 v[14:17], v[168:171], v[204:207], 0
	v_mfma_f32_16x16x32_bf16 v[6:9], v[160:163], v[212:215], 0
	v_mfma_f32_16x16x32_bf16 v[2:5], v[168:171], v[212:215], 0
	v_mfma_f32_16x16x32_bf16 v[54:57], v[164:167], v[180:183], v[54:57]
	v_mfma_f32_16x16x32_bf16 v[46:49], v[172:175], v[180:183], v[46:49]
	v_mfma_f32_16x16x32_bf16 v[38:41], v[164:167], v[188:191], v[38:41]
	v_mfma_f32_16x16x32_bf16 v[30:33], v[172:175], v[188:191], v[30:33]
	v_mfma_f32_16x16x32_bf16 v[22:25], v[164:167], v[208:211], v[22:25]
	v_mfma_f32_16x16x32_bf16 v[14:17], v[172:175], v[208:211], v[14:17]
	v_mfma_f32_16x16x32_bf16 v[6:9], v[164:167], v[216:219], v[6:9]
	v_mfma_f32_16x16x32_bf16 v[2:5], v[172:175], v[216:219], v[2:5]
	s_setprio 0
	s_barrier
	ds_read_b128 v[144:147], v253 offset:32768
	ds_read_b128 v[148:151], v253 offset:33792
	ds_read_b128 v[152:155], v253 offset:34816
	ds_read_b128 v[156:159], v253 offset:35840
	ds_read_b128 v[160:163], v253 offset:49152
	ds_read_b128 v[164:167], v253 offset:50176
	ds_read_b128 v[168:171], v253 offset:51200
	ds_read_b128 v[172:175], v253 offset:52224
	s_mov_b32 m0, s46
	ds_read_b128 v[176:179], v141 offset:32768
	ds_read_b128 v[180:183], v141 offset:33792
	ds_read_b128 v[184:187], v141 offset:34816
	ds_read_b128 v[188:191], v141 offset:35840
	ds_read_b128 v[204:207], v141 offset:36864
	ds_read_b128 v[208:211], v141 offset:37888
	ds_read_b128 v[212:215], v141 offset:38912
	ds_read_b128 v[216:219], v141 offset:39936
	global_load_lds_dwordx4 v134, s[36:37]
	s_mov_b32 m0, s54
	s_nop 0
	global_load_lds_dwordx4 v132, s[36:37]
	s_waitcnt vmcnt(8)
	s_waitcnt lgkmcnt(0)
	s_barrier
	s_setprio 1
	s_waitcnt lgkmcnt(0)
	v_mfma_f32_16x16x32_bf16 v[126:129], v[144:147], v[176:179], v[126:129]
	v_mfma_f32_16x16x32_bf16 v[122:125], v[152:155], v[176:179], v[122:125]
	v_mfma_f32_16x16x32_bf16 v[114:117], v[144:147], v[184:187], v[114:117]
	v_mfma_f32_16x16x32_bf16 v[106:109], v[152:155], v[184:187], v[106:109]
	v_mfma_f32_16x16x32_bf16 v[98:101], v[144:147], v[204:207], v[98:101]
	v_mfma_f32_16x16x32_bf16 v[90:93], v[152:155], v[204:207], v[90:93]
	v_mfma_f32_16x16x32_bf16 v[82:85], v[144:147], v[212:215], v[82:85]
	v_mfma_f32_16x16x32_bf16 v[74:77], v[152:155], v[212:215], v[74:77]
	v_mfma_f32_16x16x32_bf16 v[126:129], v[148:151], v[180:183], v[126:129]
	v_mfma_f32_16x16x32_bf16 v[122:125], v[156:159], v[180:183], v[122:125]
	v_mfma_f32_16x16x32_bf16 v[114:117], v[148:151], v[188:191], v[114:117]
	v_mfma_f32_16x16x32_bf16 v[106:109], v[156:159], v[188:191], v[106:109]
	v_mfma_f32_16x16x32_bf16 v[98:101], v[148:151], v[208:211], v[98:101]
	v_mfma_f32_16x16x32_bf16 v[90:93], v[156:159], v[208:211], v[90:93]
	v_mfma_f32_16x16x32_bf16 v[82:85], v[148:151], v[216:219], v[82:85]
	v_mfma_f32_16x16x32_bf16 v[74:77], v[156:159], v[216:219], v[74:77]
	s_setprio 0
	s_setprio 1
	v_mfma_f32_16x16x32_bf16 v[118:121], v[160:163], v[176:179], v[118:121]
	v_mfma_f32_16x16x32_bf16 v[110:113], v[168:171], v[176:179], v[110:113]
	v_mfma_f32_16x16x32_bf16 v[102:105], v[160:163], v[184:187], v[102:105]
	v_mfma_f32_16x16x32_bf16 v[94:97], v[168:171], v[184:187], v[94:97]
	v_mfma_f32_16x16x32_bf16 v[86:89], v[160:163], v[204:207], v[86:89]
	v_mfma_f32_16x16x32_bf16 v[78:81], v[168:171], v[204:207], v[78:81]
	v_mfma_f32_16x16x32_bf16 v[70:73], v[160:163], v[212:215], v[70:73]
	v_mfma_f32_16x16x32_bf16 v[66:69], v[168:171], v[212:215], v[66:69]
	v_mfma_f32_16x16x32_bf16 v[118:121], v[164:167], v[180:183], v[118:121]
	v_mfma_f32_16x16x32_bf16 v[110:113], v[172:175], v[180:183], v[110:113]
	v_mfma_f32_16x16x32_bf16 v[102:105], v[164:167], v[188:191], v[102:105]
	v_mfma_f32_16x16x32_bf16 v[94:97], v[172:175], v[188:191], v[94:97]
	v_mfma_f32_16x16x32_bf16 v[86:89], v[164:167], v[208:211], v[86:89]
	v_mfma_f32_16x16x32_bf16 v[78:81], v[172:175], v[208:211], v[78:81]
	v_mfma_f32_16x16x32_bf16 v[70:73], v[164:167], v[216:219], v[70:73]
	v_mfma_f32_16x16x32_bf16 v[66:69], v[172:175], v[216:219], v[66:69]
	s_setprio 0
	s_barrier
	s_add_u32 s100, s38, 0x80
	s_addc_u32 s101, s39, 0
	s_add_u32 s98, s42, 0x80
	s_addc_u32 s99, s43, 0
	s_mov_b32 m0, s45
	ds_read_b128 v[176:179], v141 offset:49152
	ds_read_b128 v[180:183], v141 offset:50176
	ds_read_b128 v[184:187], v141 offset:51200
	ds_read_b128 v[188:191], v141 offset:52224
	ds_read_b128 v[204:207], v141 offset:53248
	ds_read_b128 v[208:211], v141 offset:54272
	ds_read_b128 v[212:215], v141 offset:55296
	ds_read_b128 v[216:219], v141 offset:56320
	global_load_lds_dwordx4 v0, s[98:99]
	s_mov_b32 m0, s44
	s_nop 0
	global_load_lds_dwordx4 v130, s[98:99]
	s_mov_b32 m0, s65
	s_nop 0
	global_load_lds_dwordx4 v0, s[30:31]
	s_mov_b32 m0, s64
	s_nop 0
	global_load_lds_dwordx4 v130, s[30:31]
	s_mov_b32 m0, s55
	s_nop 0
	global_load_lds_dwordx4 v134, s[100:101]
	s_mov_b32 m0, s56
	s_nop 0
	global_load_lds_dwordx4 v132, s[100:101]
	s_waitcnt vmcnt(8)
	s_waitcnt lgkmcnt(0)
	s_barrier
	s_setprio 1
	s_waitcnt lgkmcnt(0)
	v_mfma_f32_16x16x32_bf16 v[62:65], v[144:147], v[176:179], v[62:65]
	v_mfma_f32_16x16x32_bf16 v[58:61], v[152:155], v[176:179], v[58:61]
	v_mfma_f32_16x16x32_bf16 v[50:53], v[144:147], v[184:187], v[50:53]
	v_mfma_f32_16x16x32_bf16 v[42:45], v[152:155], v[184:187], v[42:45]
	v_mfma_f32_16x16x32_bf16 v[34:37], v[144:147], v[204:207], v[34:37]
	v_mfma_f32_16x16x32_bf16 v[26:29], v[152:155], v[204:207], v[26:29]
	v_mfma_f32_16x16x32_bf16 v[18:21], v[144:147], v[212:215], v[18:21]
	v_mfma_f32_16x16x32_bf16 v[10:13], v[152:155], v[212:215], v[10:13]
	v_mfma_f32_16x16x32_bf16 v[62:65], v[148:151], v[180:183], v[62:65]
	v_mfma_f32_16x16x32_bf16 v[58:61], v[156:159], v[180:183], v[58:61]
	v_mfma_f32_16x16x32_bf16 v[50:53], v[148:151], v[188:191], v[50:53]
	v_mfma_f32_16x16x32_bf16 v[42:45], v[156:159], v[188:191], v[42:45]
	v_mfma_f32_16x16x32_bf16 v[34:37], v[148:151], v[208:211], v[34:37]
	v_mfma_f32_16x16x32_bf16 v[26:29], v[156:159], v[208:211], v[26:29]
	v_mfma_f32_16x16x32_bf16 v[18:21], v[148:151], v[216:219], v[18:21]
	v_mfma_f32_16x16x32_bf16 v[10:13], v[156:159], v[216:219], v[10:13]
	s_setprio 0
	s_setprio 1
	v_mfma_f32_16x16x32_bf16 v[54:57], v[160:163], v[176:179], v[54:57]
	v_mfma_f32_16x16x32_bf16 v[46:49], v[168:171], v[176:179], v[46:49]
	v_mfma_f32_16x16x32_bf16 v[38:41], v[160:163], v[184:187], v[38:41]
	v_mfma_f32_16x16x32_bf16 v[30:33], v[168:171], v[184:187], v[30:33]
	v_mfma_f32_16x16x32_bf16 v[22:25], v[160:163], v[204:207], v[22:25]
	v_mfma_f32_16x16x32_bf16 v[14:17], v[168:171], v[204:207], v[14:17]
	v_mfma_f32_16x16x32_bf16 v[6:9], v[160:163], v[212:215], v[6:9]
	v_mfma_f32_16x16x32_bf16 v[2:5], v[168:171], v[212:215], v[2:5]
	v_mfma_f32_16x16x32_bf16 v[54:57], v[164:167], v[180:183], v[54:57]
	v_mfma_f32_16x16x32_bf16 v[46:49], v[172:175], v[180:183], v[46:49]
	v_mfma_f32_16x16x32_bf16 v[38:41], v[164:167], v[188:191], v[38:41]
	v_mfma_f32_16x16x32_bf16 v[30:33], v[172:175], v[188:191], v[30:33]
	v_mfma_f32_16x16x32_bf16 v[22:25], v[164:167], v[208:211], v[22:25]
	v_mfma_f32_16x16x32_bf16 v[14:17], v[172:175], v[208:211], v[14:17]
	v_mfma_f32_16x16x32_bf16 v[6:9], v[164:167], v[216:219], v[6:9]
	v_mfma_f32_16x16x32_bf16 v[2:5], v[172:175], v[216:219], v[2:5]
	s_setprio 0
	s_barrier
	s_movk_i32 s36, 0x100
	s_andn2_b64 vcc, exec, s[26:27]
	s_mov_b64 s[30:31], -1
	s_mov_b64 s[26:27], 0
	s_cbranch_vccz .LBB0_361
	s_branch .Lpeel_exit_2

.LBB0_976:
	s_add_i32 s13, s27, -2
	s_add_u32 s38, s38, 0x80080
	s_addc_u32 s39, s39, 0
	s_add_u32 s15, s42, 0x100
	s_addc_u32 s21, s43, 0
	s_mov_b32 s33, 0
	s_waitcnt vmcnt(0)
	v_add_u32_e32 v253, 0x10000, v192
	s_add_i32 s37, s33, 2
	s_add_u32 s40, s38, 0xfff80080
	s_addc_u32 s41, s39, -1
	s_add_i32 s44, 0, 0x10000
	s_cmp_eq_u32 s13, s33
	s_cselect_b32 s51, s23, s41
	s_cselect_b32 s50, s22, s40
	s_cselect_b32 s43, s25, s21
	s_cselect_b32 s42, s24, s15
	s_add_i32 s33, 0, 0x14000
	ds_read_b128 v[122:125], v253
	ds_read_b128 v[126:129], v253 offset:1024
	ds_read_b128 v[130:133], v253 offset:2048
	ds_read_b128 v[134:137], v253 offset:3072
	ds_read_b128 v[146:149], v253 offset:16384
	ds_read_b128 v[150:153], v253 offset:17408
	ds_read_b128 v[154:157], v253 offset:18432
	ds_read_b128 v[158:161], v253 offset:19456
	s_add_i32 m0, s31, 0xc000
	ds_read_b128 v[162:165], v204
	ds_read_b128 v[176:179], v204 offset:1024
	ds_read_b128 v[180:183], v204 offset:2048
	ds_read_b128 v[184:187], v204 offset:3072
	ds_read_b128 v[206:209], v204 offset:4096
	ds_read_b128 v[210:213], v204 offset:5120
	ds_read_b128 v[214:217], v204 offset:6144
	ds_read_b128 v[218:221], v204 offset:7168
	global_load_lds_dwordx4 v172, s[38:39]
	s_add_i32 m0, s31, 0xe000
	s_nop 0
	global_load_lds_dwordx4 v174, s[38:39]
	s_waitcnt vmcnt(63)
	s_waitcnt lgkmcnt(0)
	s_barrier
	s_setprio 1
	s_waitcnt lgkmcnt(0)
	v_mfma_f32_16x16x32_bf16 v[142:145], v[122:125], v[162:165], 0
	v_mfma_f32_16x16x32_bf16 v[138:141], v[130:133], v[162:165], 0
	v_mfma_f32_16x16x32_bf16 v[118:121], v[122:125], v[180:183], 0
	v_mfma_f32_16x16x32_bf16 v[110:113], v[130:133], v[180:183], 0
	v_mfma_f32_16x16x32_bf16 v[98:101], v[122:125], v[206:209], 0
	v_mfma_f32_16x16x32_bf16 v[90:93], v[130:133], v[206:209], 0
	v_mfma_f32_16x16x32_bf16 v[82:85], v[122:125], v[214:217], 0
	v_mfma_f32_16x16x32_bf16 v[74:77], v[130:133], v[214:217], 0
	v_mfma_f32_16x16x32_bf16 v[142:145], v[126:129], v[176:179], v[142:145]
	v_mfma_f32_16x16x32_bf16 v[138:141], v[134:137], v[176:179], v[138:141]
	v_mfma_f32_16x16x32_bf16 v[118:121], v[126:129], v[184:187], v[118:121]
	v_mfma_f32_16x16x32_bf16 v[110:113], v[134:137], v[184:187], v[110:113]
	v_mfma_f32_16x16x32_bf16 v[98:101], v[126:129], v[210:213], v[98:101]
	v_mfma_f32_16x16x32_bf16 v[90:93], v[134:137], v[210:213], v[90:93]
	v_mfma_f32_16x16x32_bf16 v[82:85], v[126:129], v[218:221], v[82:85]
	v_mfma_f32_16x16x32_bf16 v[74:77], v[134:137], v[218:221], v[74:77]
	s_setprio 0
	s_setprio 1
	v_mfma_f32_16x16x32_bf16 v[114:117], v[146:149], v[162:165], 0
	v_mfma_f32_16x16x32_bf16 v[106:109], v[154:157], v[162:165], 0
	v_mfma_f32_16x16x32_bf16 v[102:105], v[146:149], v[180:183], 0
	v_mfma_f32_16x16x32_bf16 v[94:97], v[154:157], v[180:183], 0
	v_mfma_f32_16x16x32_bf16 v[86:89], v[146:149], v[206:209], 0
	v_mfma_f32_16x16x32_bf16 v[78:81], v[154:157], v[206:209], 0
	v_mfma_f32_16x16x32_bf16 v[70:73], v[146:149], v[214:217], 0
	v_mfma_f32_16x16x32_bf16 v[66:69], v[154:157], v[214:217], 0
	v_mfma_f32_16x16x32_bf16 v[114:117], v[150:153], v[176:179], v[114:117]
	v_mfma_f32_16x16x32_bf16 v[106:109], v[158:161], v[176:179], v[106:109]
	v_mfma_f32_16x16x32_bf16 v[102:105], v[150:153], v[184:187], v[102:105]
	v_mfma_f32_16x16x32_bf16 v[94:97], v[158:161], v[184:187], v[94:97]
	v_mfma_f32_16x16x32_bf16 v[86:89], v[150:153], v[210:213], v[86:89]
	v_mfma_f32_16x16x32_bf16 v[78:81], v[158:161], v[210:213], v[78:81]
	v_mfma_f32_16x16x32_bf16 v[70:73], v[150:153], v[218:221], v[70:73]
	v_mfma_f32_16x16x32_bf16 v[66:69], v[158:161], v[218:221], v[66:69]
	s_setprio 0
	s_barrier
	s_add_i32 s40, s44, s19
	s_mov_b32 m0, s40
	ds_read_b128 v[162:165], v204 offset:16384
	ds_read_b128 v[176:179], v204 offset:17408
	ds_read_b128 v[180:183], v204 offset:18432
	ds_read_b128 v[184:187], v204 offset:19456
	ds_read_b128 v[206:209], v204 offset:20480
	ds_read_b128 v[210:213], v204 offset:21504
	ds_read_b128 v[214:217], v204 offset:22528
	ds_read_b128 v[218:221], v204 offset:23552
	global_load_lds_dwordx4 v0, s[42:43]
	s_add_i32 m0, s40, 0x2000
	s_add_u32 s40, s42, 0x80000
	s_addc_u32 s41, s43, 0
	s_add_i32 s33, s33, s19
	global_load_lds_dwordx4 v170, s[42:43]
	s_mov_b32 m0, s33
	s_nop 0
	global_load_lds_dwordx4 v0, s[40:41]
	s_add_i32 m0, s33, 0x2000
	s_nop 0
	global_load_lds_dwordx4 v170, s[40:41]
	s_mov_b32 m0, s31
	s_nop 0
	global_load_lds_dwordx4 v166, s[50:51]
	s_mov_b32 m0, s34
	s_nop 0
	global_load_lds_dwordx4 v168, s[50:51]
	s_waitcnt vmcnt(8)
	s_waitcnt lgkmcnt(0)
	s_barrier
	s_setprio 1
	s_waitcnt lgkmcnt(0)
	v_mfma_f32_16x16x32_bf16 v[62:65], v[122:125], v[162:165], 0
	v_mfma_f32_16x16x32_bf16 v[58:61], v[130:133], v[162:165], 0
	v_mfma_f32_16x16x32_bf16 v[50:53], v[122:125], v[180:183], 0
	v_mfma_f32_16x16x32_bf16 v[42:45], v[130:133], v[180:183], 0
	v_mfma_f32_16x16x32_bf16 v[34:37], v[122:125], v[206:209], 0
	v_mfma_f32_16x16x32_bf16 v[26:29], v[130:133], v[206:209], 0
	v_mfma_f32_16x16x32_bf16 v[18:21], v[122:125], v[214:217], 0
	v_mfma_f32_16x16x32_bf16 v[10:13], v[130:133], v[214:217], 0
	v_mfma_f32_16x16x32_bf16 v[62:65], v[126:129], v[176:179], v[62:65]
	v_mfma_f32_16x16x32_bf16 v[58:61], v[134:137], v[176:179], v[58:61]
	v_mfma_f32_16x16x32_bf16 v[50:53], v[126:129], v[184:187], v[50:53]
	v_mfma_f32_16x16x32_bf16 v[42:45], v[134:137], v[184:187], v[42:45]
	v_mfma_f32_16x16x32_bf16 v[34:37], v[126:129], v[210:213], v[34:37]
	v_mfma_f32_16x16x32_bf16 v[26:29], v[134:137], v[210:213], v[26:29]
	v_mfma_f32_16x16x32_bf16 v[18:21], v[126:129], v[218:221], v[18:21]
	v_mfma_f32_16x16x32_bf16 v[10:13], v[134:137], v[218:221], v[10:13]
	s_setprio 0
	s_setprio 1
	v_mfma_f32_16x16x32_bf16 v[54:57], v[146:149], v[162:165], 0
	v_mfma_f32_16x16x32_bf16 v[46:49], v[154:157], v[162:165], 0
	v_mfma_f32_16x16x32_bf16 v[38:41], v[146:149], v[180:183], 0
	v_mfma_f32_16x16x32_bf16 v[30:33], v[154:157], v[180:183], 0
	v_mfma_f32_16x16x32_bf16 v[22:25], v[146:149], v[206:209], 0
	v_mfma_f32_16x16x32_bf16 v[14:17], v[154:157], v[206:209], 0
	v_mfma_f32_16x16x32_bf16 v[6:9], v[146:149], v[214:217], 0
	v_mfma_f32_16x16x32_bf16 v[2:5], v[154:157], v[214:217], 0
	v_mfma_f32_16x16x32_bf16 v[54:57], v[150:153], v[176:179], v[54:57]
	v_mfma_f32_16x16x32_bf16 v[46:49], v[158:161], v[176:179], v[46:49]
	v_mfma_f32_16x16x32_bf16 v[38:41], v[150:153], v[184:187], v[38:41]
	v_mfma_f32_16x16x32_bf16 v[30:33], v[158:161], v[184:187], v[30:33]
	v_mfma_f32_16x16x32_bf16 v[22:25], v[150:153], v[210:213], v[22:25]
	v_mfma_f32_16x16x32_bf16 v[14:17], v[158:161], v[210:213], v[14:17]
	v_mfma_f32_16x16x32_bf16 v[6:9], v[150:153], v[218:221], v[6:9]
	v_mfma_f32_16x16x32_bf16 v[2:5], v[158:161], v[218:221], v[2:5]
	s_setprio 0
	s_barrier
	s_add_i32 s33, 0, 0x18000
	s_add_i32 s44, 0, 0x1c000
	ds_read_b128 v[122:125], v253 offset:32768
	ds_read_b128 v[126:129], v253 offset:33792
	ds_read_b128 v[130:133], v253 offset:34816
	ds_read_b128 v[134:137], v253 offset:35840
	ds_read_b128 v[146:149], v253 offset:49152
	ds_read_b128 v[150:153], v253 offset:50176
	ds_read_b128 v[154:157], v253 offset:51200
	ds_read_b128 v[158:161], v253 offset:52224
	s_add_u32 s40, s50, 0x80000
	s_addc_u32 s41, s51, 0
	s_mov_b32 m0, s35
	ds_read_b128 v[162:165], v204 offset:32768
	ds_read_b128 v[176:179], v204 offset:33792
	ds_read_b128 v[180:183], v204 offset:34816
	ds_read_b128 v[184:187], v204 offset:35840
	ds_read_b128 v[206:209], v204 offset:36864
	ds_read_b128 v[210:213], v204 offset:37888
	ds_read_b128 v[214:217], v204 offset:38912
	ds_read_b128 v[218:221], v204 offset:39936
	global_load_lds_dwordx4 v166, s[40:41]
	s_mov_b32 m0, s46
	s_nop 0
	global_load_lds_dwordx4 v168, s[40:41]
	s_waitcnt vmcnt(8)
	s_waitcnt lgkmcnt(0)
	s_barrier
	s_setprio 1
	s_waitcnt lgkmcnt(0)
	v_mfma_f32_16x16x32_bf16 v[142:145], v[122:125], v[162:165], v[142:145]
	v_mfma_f32_16x16x32_bf16 v[138:141], v[130:133], v[162:165], v[138:141]
	v_mfma_f32_16x16x32_bf16 v[118:121], v[122:125], v[180:183], v[118:121]
	v_mfma_f32_16x16x32_bf16 v[110:113], v[130:133], v[180:183], v[110:113]
	v_mfma_f32_16x16x32_bf16 v[98:101], v[122:125], v[206:209], v[98:101]
	v_mfma_f32_16x16x32_bf16 v[90:93], v[130:133], v[206:209], v[90:93]
	v_mfma_f32_16x16x32_bf16 v[82:85], v[122:125], v[214:217], v[82:85]
	v_mfma_f32_16x16x32_bf16 v[74:77], v[130:133], v[214:217], v[74:77]
	v_mfma_f32_16x16x32_bf16 v[142:145], v[126:129], v[176:179], v[142:145]
	v_mfma_f32_16x16x32_bf16 v[138:141], v[134:137], v[176:179], v[138:141]
	v_mfma_f32_16x16x32_bf16 v[118:121], v[126:129], v[184:187], v[118:121]
	v_mfma_f32_16x16x32_bf16 v[110:113], v[134:137], v[184:187], v[110:113]
	v_mfma_f32_16x16x32_bf16 v[98:101], v[126:129], v[210:213], v[98:101]
	v_mfma_f32_16x16x32_bf16 v[90:93], v[134:137], v[210:213], v[90:93]
	v_mfma_f32_16x16x32_bf16 v[82:85], v[126:129], v[218:221], v[82:85]
	v_mfma_f32_16x16x32_bf16 v[74:77], v[134:137], v[218:221], v[74:77]
	s_setprio 0
	s_setprio 1
	v_mfma_f32_16x16x32_bf16 v[114:117], v[146:149], v[162:165], v[114:117]
	v_mfma_f32_16x16x32_bf16 v[106:109], v[154:157], v[162:165], v[106:109]
	v_mfma_f32_16x16x32_bf16 v[102:105], v[146:149], v[180:183], v[102:105]
	v_mfma_f32_16x16x32_bf16 v[94:97], v[154:157], v[180:183], v[94:97]
	v_mfma_f32_16x16x32_bf16 v[86:89], v[146:149], v[206:209], v[86:89]
	v_mfma_f32_16x16x32_bf16 v[78:81], v[154:157], v[206:209], v[78:81]
	v_mfma_f32_16x16x32_bf16 v[70:73], v[146:149], v[214:217], v[70:73]
	v_mfma_f32_16x16x32_bf16 v[66:69], v[154:157], v[214:217], v[66:69]
	v_mfma_f32_16x16x32_bf16 v[114:117], v[150:153], v[176:179], v[114:117]
	v_mfma_f32_16x16x32_bf16 v[106:109], v[158:161], v[176:179], v[106:109]
	v_mfma_f32_16x16x32_bf16 v[102:105], v[150:153], v[184:187], v[102:105]
	v_mfma_f32_16x16x32_bf16 v[94:97], v[158:161], v[184:187], v[94:97]
	v_mfma_f32_16x16x32_bf16 v[86:89], v[150:153], v[210:213], v[86:89]
	v_mfma_f32_16x16x32_bf16 v[78:81], v[158:161], v[210:213], v[78:81]
	v_mfma_f32_16x16x32_bf16 v[70:73], v[150:153], v[218:221], v[70:73]
	v_mfma_f32_16x16x32_bf16 v[66:69], v[158:161], v[218:221], v[66:69]
	s_setprio 0
	s_barrier
	s_add_u32 s100, s40, 0xfff80080
	s_addc_u32 s101, s41, -1
	s_add_u32 s98, s42, 0x80
	s_addc_u32 s99, s43, 0
	s_add_i32 s33, s33, s19
	s_mov_b32 m0, s33
	ds_read_b128 v[162:165], v204 offset:49152
	ds_read_b128 v[176:179], v204 offset:50176
	ds_read_b128 v[180:183], v204 offset:51200
	ds_read_b128 v[184:187], v204 offset:52224
	ds_read_b128 v[206:209], v204 offset:53248
	ds_read_b128 v[210:213], v204 offset:54272
	ds_read_b128 v[214:217], v204 offset:55296
	ds_read_b128 v[218:221], v204 offset:56320
	global_load_lds_dwordx4 v0, s[98:99]
	s_add_i32 m0, s33, 0x2000
	s_add_u32 s40, s42, 0x80080
	s_addc_u32 s41, s43, 0
	s_add_i32 s33, s44, s19
	global_load_lds_dwordx4 v170, s[98:99]
	s_mov_b32 m0, s33
	s_nop 0
	global_load_lds_dwordx4 v0, s[40:41]
	s_add_i32 m0, s33, 0x2000
	s_nop 0
	global_load_lds_dwordx4 v170, s[40:41]
	s_mov_b32 m0, s54
	s_nop 0
	global_load_lds_dwordx4 v166, s[100:101]
	s_mov_b32 m0, s55
	s_nop 0
	global_load_lds_dwordx4 v168, s[100:101]
	s_waitcnt vmcnt(8)
	s_waitcnt lgkmcnt(0)
	s_barrier
	s_setprio 1
	s_waitcnt lgkmcnt(0)
	v_mfma_f32_16x16x32_bf16 v[62:65], v[122:125], v[162:165], v[62:65]
	v_mfma_f32_16x16x32_bf16 v[58:61], v[130:133], v[162:165], v[58:61]
	v_mfma_f32_16x16x32_bf16 v[50:53], v[122:125], v[180:183], v[50:53]
	v_mfma_f32_16x16x32_bf16 v[42:45], v[130:133], v[180:183], v[42:45]
	v_mfma_f32_16x16x32_bf16 v[34:37], v[122:125], v[206:209], v[34:37]
	v_mfma_f32_16x16x32_bf16 v[26:29], v[130:133], v[206:209], v[26:29]
	v_mfma_f32_16x16x32_bf16 v[18:21], v[122:125], v[214:217], v[18:21]
	v_mfma_f32_16x16x32_bf16 v[10:13], v[130:133], v[214:217], v[10:13]
	v_mfma_f32_16x16x32_bf16 v[62:65], v[126:129], v[176:179], v[62:65]
	v_mfma_f32_16x16x32_bf16 v[58:61], v[134:137], v[176:179], v[58:61]
	v_mfma_f32_16x16x32_bf16 v[50:53], v[126:129], v[184:187], v[50:53]
	v_mfma_f32_16x16x32_bf16 v[42:45], v[134:137], v[184:187], v[42:45]
	v_mfma_f32_16x16x32_bf16 v[34:37], v[126:129], v[210:213], v[34:37]
	v_mfma_f32_16x16x32_bf16 v[26:29], v[134:137], v[210:213], v[26:29]
	v_mfma_f32_16x16x32_bf16 v[18:21], v[126:129], v[218:221], v[18:21]
	v_mfma_f32_16x16x32_bf16 v[10:13], v[134:137], v[218:221], v[10:13]
	s_setprio 0
	s_setprio 1
	v_mfma_f32_16x16x32_bf16 v[54:57], v[146:149], v[162:165], v[54:57]
	v_mfma_f32_16x16x32_bf16 v[46:49], v[154:157], v[162:165], v[46:49]
	v_mfma_f32_16x16x32_bf16 v[38:41], v[146:149], v[180:183], v[38:41]
	v_mfma_f32_16x16x32_bf16 v[30:33], v[154:157], v[180:183], v[30:33]
	v_mfma_f32_16x16x32_bf16 v[22:25], v[146:149], v[206:209], v[22:25]
	v_mfma_f32_16x16x32_bf16 v[14:17], v[154:157], v[206:209], v[14:17]
	v_mfma_f32_16x16x32_bf16 v[6:9], v[146:149], v[214:217], v[6:9]
	v_mfma_f32_16x16x32_bf16 v[2:5], v[154:157], v[214:217], v[2:5]
	v_mfma_f32_16x16x32_bf16 v[54:57], v[150:153], v[176:179], v[54:57]
	v_mfma_f32_16x16x32_bf16 v[46:49], v[158:161], v[176:179], v[46:49]
	v_mfma_f32_16x16x32_bf16 v[38:41], v[150:153], v[184:187], v[38:41]
	v_mfma_f32_16x16x32_bf16 v[30:33], v[158:161], v[184:187], v[30:33]
	v_mfma_f32_16x16x32_bf16 v[22:25], v[150:153], v[210:213], v[22:25]
	v_mfma_f32_16x16x32_bf16 v[14:17], v[158:161], v[210:213], v[14:17]
	v_mfma_f32_16x16x32_bf16 v[6:9], v[150:153], v[218:221], v[6:9]
	v_mfma_f32_16x16x32_bf16 v[2:5], v[158:161], v[218:221], v[2:5]
	s_setprio 0
	s_barrier
	s_add_u32 s38, s38, 0x100
	s_addc_u32 s39, s39, 0
	s_add_u32 s15, s15, 0x100
	s_addc_u32 s21, s21, 0
	s_cmp_ge_u32 s37, s27
	s_mov_b32 s33, s37
	s_cbranch_scc0 .LBB0_977
	s_branch .Lpeel_exit_3

.LBB0_1079:
	s_ashr_i32 s43, s42, 31
	s_lshl_b64 s[40:41], s[42:43], 20
	s_add_u32 s50, s19, s40
	s_addc_u32 s51, s28, s41
	s_and_b64 s[40:41], s[8:9], exec
	s_cselect_b32 s11, s51, s57
	s_cselect_b32 s33, s50, s56
	s_ashr_i32 s39, s38, 31
	s_lshl_b64 s[40:41], s[38:39], 20
	s_add_u32 s52, s29, s40
	s_addc_u32 s53, s34, s41
	s_and_b64 s[40:41], s[8:9], exec
	s_cselect_b32 s39, s53, s61
	s_cselect_b32 s40, s52, s60
	s_add_u32 s41, s60, 0x100
	s_addc_u32 s43, s61, 0
	s_mov_b32 s44, -2
	v_add_u32_e32 v253, 0x10000, v223
	s_add_u32 s60, s56, 0x100
	s_addc_u32 s61, s57, 0
	s_add_i32 s45, 0, 0x10000
	s_cmp_eq_u32 s44, 28
	s_cselect_b32 s65, s11, s61
	s_cselect_b32 s64, s33, s60
	s_cselect_b32 s63, s39, s43
	s_cselect_b32 s62, s40, s41
	s_add_i32 s55, 0, 0x14000
	ds_read_b128 v[62:65], v253
	ds_read_b128 v[66:69], v253 offset:1024
	ds_read_b128 v[106:109], v253 offset:2048
	ds_read_b128 v[110:113], v253 offset:3072
	ds_read_b128 v[138:141], v253 offset:16384
	ds_read_b128 v[150:153], v253 offset:17408
	ds_read_b128 v[154:157], v253 offset:18432
	ds_read_b128 v[158:161], v253 offset:19456
	s_add_i32 m0, s46, 0xc000
	ds_read_b128 v[162:165], v227
	ds_read_b128 v[166:169], v227 offset:1024
	ds_read_b128 v[170:173], v227 offset:2048
	ds_read_b128 v[174:177], v227 offset:3072
	ds_read_b128 v[178:181], v227 offset:4096
	ds_read_b128 v[182:185], v227 offset:5120
	ds_read_b128 v[186:189], v227 offset:6144
	ds_read_b128 v[190:193], v227 offset:7168
	global_load_lds_dwordx4 v210, s[56:57]
	s_add_i32 m0, s46, 0xe000
	s_nop 0
	global_load_lds_dwordx4 v212, s[56:57]
	s_waitcnt vmcnt(63)
	s_waitcnt lgkmcnt(0)
	s_barrier
	s_setprio 1
	s_waitcnt lgkmcnt(0)
	v_mfma_f32_16x16x32_bf16 v[146:149], v[62:65], v[162:165], 0
	v_mfma_f32_16x16x32_bf16 v[70:73], v[106:109], v[162:165], 0
	v_mfma_f32_16x16x32_bf16 v[134:137], v[62:65], v[170:173], 0
	v_mfma_f32_16x16x32_bf16 v[54:57], v[106:109], v[170:173], 0
	v_mfma_f32_16x16x32_bf16 v[126:129], v[62:65], v[178:181], 0
	v_mfma_f32_16x16x32_bf16 v[46:49], v[106:109], v[178:181], 0
	v_mfma_f32_16x16x32_bf16 v[118:121], v[62:65], v[186:189], 0
	v_mfma_f32_16x16x32_bf16 v[38:41], v[106:109], v[186:189], 0
	v_mfma_f32_16x16x32_bf16 v[146:149], v[66:69], v[166:169], v[146:149]
	v_mfma_f32_16x16x32_bf16 v[70:73], v[110:113], v[166:169], v[70:73]
	v_mfma_f32_16x16x32_bf16 v[134:137], v[66:69], v[174:177], v[134:137]
	v_mfma_f32_16x16x32_bf16 v[54:57], v[110:113], v[174:177], v[54:57]
	v_mfma_f32_16x16x32_bf16 v[126:129], v[66:69], v[182:185], v[126:129]
	v_mfma_f32_16x16x32_bf16 v[46:49], v[110:113], v[182:185], v[46:49]
	v_mfma_f32_16x16x32_bf16 v[118:121], v[66:69], v[190:193], v[118:121]
	v_mfma_f32_16x16x32_bf16 v[38:41], v[110:113], v[190:193], v[38:41]
	s_setprio 0
	s_setprio 1
	v_mfma_f32_16x16x32_bf16 v[142:145], v[138:141], v[162:165], 0
	v_mfma_f32_16x16x32_bf16 v[58:61], v[154:157], v[162:165], 0
	v_mfma_f32_16x16x32_bf16 v[130:133], v[138:141], v[170:173], 0
	v_mfma_f32_16x16x32_bf16 v[50:53], v[154:157], v[170:173], 0
	v_mfma_f32_16x16x32_bf16 v[122:125], v[138:141], v[178:181], 0
	v_mfma_f32_16x16x32_bf16 v[42:45], v[154:157], v[178:181], 0
	v_mfma_f32_16x16x32_bf16 v[114:117], v[138:141], v[186:189], 0
	v_mfma_f32_16x16x32_bf16 v[34:37], v[154:157], v[186:189], 0
	v_mfma_f32_16x16x32_bf16 v[142:145], v[150:153], v[166:169], v[142:145]
	v_mfma_f32_16x16x32_bf16 v[58:61], v[158:161], v[166:169], v[58:61]
	v_mfma_f32_16x16x32_bf16 v[130:133], v[150:153], v[174:177], v[130:133]
	v_mfma_f32_16x16x32_bf16 v[50:53], v[158:161], v[174:177], v[50:53]
	v_mfma_f32_16x16x32_bf16 v[122:125], v[150:153], v[182:185], v[122:125]
	v_mfma_f32_16x16x32_bf16 v[42:45], v[158:161], v[182:185], v[42:45]
	v_mfma_f32_16x16x32_bf16 v[114:117], v[150:153], v[190:193], v[114:117]
	v_mfma_f32_16x16x32_bf16 v[34:37], v[158:161], v[190:193], v[34:37]
	s_setprio 0
	s_barrier
	s_add_i32 s45, s45, s35
	s_mov_b32 m0, s45
	ds_read_b128 v[162:165], v227 offset:16384
	ds_read_b128 v[166:169], v227 offset:17408
	ds_read_b128 v[170:173], v227 offset:18432
	ds_read_b128 v[174:177], v227 offset:19456
	ds_read_b128 v[178:181], v227 offset:20480
	ds_read_b128 v[182:185], v227 offset:21504
	ds_read_b128 v[186:189], v227 offset:22528
	ds_read_b128 v[190:193], v227 offset:23552
	global_load_lds_dwordx4 v0, s[62:63]
	s_add_i32 m0, s45, 0x2000
	s_add_u32 s56, s62, 0x80000
	s_addc_u32 s57, s63, 0
	s_add_i32 s45, s55, s35
	global_load_lds_dwordx4 v208, s[62:63]
	s_mov_b32 m0, s45
	s_nop 0
	global_load_lds_dwordx4 v0, s[56:57]
	s_add_i32 m0, s45, 0x2000
	s_nop 0
	global_load_lds_dwordx4 v208, s[56:57]
	s_mov_b32 m0, s46
	s_nop 0
	global_load_lds_dwordx4 v204, s[64:65]
	s_mov_b32 m0, s66
	s_nop 0
	global_load_lds_dwordx4 v206, s[64:65]
	s_waitcnt vmcnt(8)
	s_waitcnt lgkmcnt(0)
	s_barrier
	s_setprio 1
	s_waitcnt lgkmcnt(0)
	v_mfma_f32_16x16x32_bf16 v[102:105], v[62:65], v[162:165], 0
	v_mfma_f32_16x16x32_bf16 v[30:33], v[106:109], v[162:165], 0
	v_mfma_f32_16x16x32_bf16 v[94:97], v[62:65], v[170:173], 0
	v_mfma_f32_16x16x32_bf16 v[22:25], v[106:109], v[170:173], 0
	v_mfma_f32_16x16x32_bf16 v[86:89], v[62:65], v[178:181], 0
	v_mfma_f32_16x16x32_bf16 v[14:17], v[106:109], v[178:181], 0
	v_mfma_f32_16x16x32_bf16 v[10:13], v[106:109], v[186:189], 0
	v_mfma_f32_16x16x32_bf16 v[102:105], v[66:69], v[166:169], v[102:105]
	v_mfma_f32_16x16x32_bf16 v[30:33], v[110:113], v[166:169], v[30:33]
	v_mfma_f32_16x16x32_bf16 v[94:97], v[66:69], v[174:177], v[94:97]
	v_mfma_f32_16x16x32_bf16 v[22:25], v[110:113], v[174:177], v[22:25]
	v_mfma_f32_16x16x32_bf16 v[86:89], v[66:69], v[182:185], v[86:89]
	v_mfma_f32_16x16x32_bf16 v[14:17], v[110:113], v[182:185], v[14:17]
	v_mfma_f32_16x16x32_bf16 v[62:65], v[62:65], v[186:189], 0
	v_mfma_f32_16x16x32_bf16 v[10:13], v[110:113], v[190:193], v[10:13]
	v_mfma_f32_16x16x32_bf16 v[62:65], v[66:69], v[190:193], v[62:65]
	s_setprio 0
	s_setprio 1
	v_mfma_f32_16x16x32_bf16 v[26:29], v[154:157], v[162:165], 0
	v_mfma_f32_16x16x32_bf16 v[82:85], v[138:141], v[170:173], 0
	v_mfma_f32_16x16x32_bf16 v[18:21], v[154:157], v[170:173], 0
	v_mfma_f32_16x16x32_bf16 v[78:81], v[138:141], v[178:181], 0
	v_mfma_f32_16x16x32_bf16 v[6:9], v[154:157], v[178:181], 0
	v_mfma_f32_16x16x32_bf16 v[74:77], v[138:141], v[186:189], 0
	v_mfma_f32_16x16x32_bf16 v[2:5], v[154:157], v[186:189], 0
	v_mfma_f32_16x16x32_bf16 v[66:69], v[138:141], v[162:165], 0
	v_mfma_f32_16x16x32_bf16 v[26:29], v[158:161], v[166:169], v[26:29]
	v_mfma_f32_16x16x32_bf16 v[90:93], v[150:153], v[174:177], v[82:85]
	v_mfma_f32_16x16x32_bf16 v[18:21], v[158:161], v[174:177], v[18:21]
	v_mfma_f32_16x16x32_bf16 v[78:81], v[150:153], v[182:185], v[78:81]
	v_mfma_f32_16x16x32_bf16 v[6:9], v[158:161], v[182:185], v[6:9]
	v_mfma_f32_16x16x32_bf16 v[74:77], v[150:153], v[190:193], v[74:77]
	v_mfma_f32_16x16x32_bf16 v[2:5], v[158:161], v[190:193], v[2:5]
	v_mfma_f32_16x16x32_bf16 v[66:69], v[150:153], v[166:169], v[66:69]
	s_setprio 0
	s_barrier
	s_add_i32 s45, 0, 0x18000
	s_add_i32 s55, 0, 0x1c000
	ds_read_b128 v[82:85], v253 offset:32768
	ds_read_b128 v[98:101], v253 offset:33792
	ds_read_b128 v[106:109], v253 offset:34816
	ds_read_b128 v[110:113], v253 offset:35840
	ds_read_b128 v[138:141], v253 offset:49152
	ds_read_b128 v[150:153], v253 offset:50176
	ds_read_b128 v[154:157], v253 offset:51200
	ds_read_b128 v[158:161], v253 offset:52224
	s_add_u32 s56, s64, 0x4000
	s_addc_u32 s57, s65, 0
	s_mov_b32 m0, s67
	ds_read_b128 v[162:165], v227 offset:32768
	ds_read_b128 v[166:169], v227 offset:33792
	ds_read_b128 v[170:173], v227 offset:34816
	ds_read_b128 v[174:177], v227 offset:35840
	ds_read_b128 v[178:181], v227 offset:36864
	ds_read_b128 v[182:185], v227 offset:37888
	ds_read_b128 v[186:189], v227 offset:38912
	ds_read_b128 v[190:193], v227 offset:39936
	global_load_lds_dwordx4 v204, s[56:57]
	s_mov_b32 m0, s68
	s_nop 0
	global_load_lds_dwordx4 v206, s[56:57]
	s_waitcnt vmcnt(8)
	s_waitcnt lgkmcnt(0)
	s_barrier
	s_setprio 1
	s_waitcnt lgkmcnt(0)
	v_mfma_f32_16x16x32_bf16 v[146:149], v[82:85], v[162:165], v[146:149]
	v_mfma_f32_16x16x32_bf16 v[70:73], v[106:109], v[162:165], v[70:73]
	v_mfma_f32_16x16x32_bf16 v[134:137], v[82:85], v[170:173], v[134:137]
	v_mfma_f32_16x16x32_bf16 v[54:57], v[106:109], v[170:173], v[54:57]
	v_mfma_f32_16x16x32_bf16 v[126:129], v[82:85], v[178:181], v[126:129]
	v_mfma_f32_16x16x32_bf16 v[46:49], v[106:109], v[178:181], v[46:49]
	v_mfma_f32_16x16x32_bf16 v[118:121], v[82:85], v[186:189], v[118:121]
	v_mfma_f32_16x16x32_bf16 v[38:41], v[106:109], v[186:189], v[38:41]
	v_mfma_f32_16x16x32_bf16 v[146:149], v[98:101], v[166:169], v[146:149]
	v_mfma_f32_16x16x32_bf16 v[70:73], v[110:113], v[166:169], v[70:73]
	v_mfma_f32_16x16x32_bf16 v[134:137], v[98:101], v[174:177], v[134:137]
	v_mfma_f32_16x16x32_bf16 v[54:57], v[110:113], v[174:177], v[54:57]
	v_mfma_f32_16x16x32_bf16 v[126:129], v[98:101], v[182:185], v[126:129]
	v_mfma_f32_16x16x32_bf16 v[46:49], v[110:113], v[182:185], v[46:49]
	v_mfma_f32_16x16x32_bf16 v[118:121], v[98:101], v[190:193], v[118:121]
	v_mfma_f32_16x16x32_bf16 v[38:41], v[110:113], v[190:193], v[38:41]
	s_setprio 0
	s_setprio 1
	v_mfma_f32_16x16x32_bf16 v[142:145], v[138:141], v[162:165], v[142:145]
	v_mfma_f32_16x16x32_bf16 v[58:61], v[154:157], v[162:165], v[58:61]
	v_mfma_f32_16x16x32_bf16 v[130:133], v[138:141], v[170:173], v[130:133]
	v_mfma_f32_16x16x32_bf16 v[50:53], v[154:157], v[170:173], v[50:53]
	v_mfma_f32_16x16x32_bf16 v[122:125], v[138:141], v[178:181], v[122:125]
	v_mfma_f32_16x16x32_bf16 v[42:45], v[154:157], v[178:181], v[42:45]
	v_mfma_f32_16x16x32_bf16 v[114:117], v[138:141], v[186:189], v[114:117]
	v_mfma_f32_16x16x32_bf16 v[34:37], v[154:157], v[186:189], v[34:37]
	v_mfma_f32_16x16x32_bf16 v[142:145], v[150:153], v[166:169], v[142:145]
	v_mfma_f32_16x16x32_bf16 v[58:61], v[158:161], v[166:169], v[58:61]
	v_mfma_f32_16x16x32_bf16 v[130:133], v[150:153], v[174:177], v[130:133]
	v_mfma_f32_16x16x32_bf16 v[50:53], v[158:161], v[174:177], v[50:53]
	v_mfma_f32_16x16x32_bf16 v[122:125], v[150:153], v[182:185], v[122:125]
	v_mfma_f32_16x16x32_bf16 v[42:45], v[158:161], v[182:185], v[42:45]
	v_mfma_f32_16x16x32_bf16 v[114:117], v[150:153], v[190:193], v[114:117]
	v_mfma_f32_16x16x32_bf16 v[34:37], v[158:161], v[190:193], v[34:37]
	s_setprio 0
	s_barrier
	s_add_u32 s100, s56, 0xffffc080
	s_addc_u32 s101, s57, -1
	s_add_u32 s98, s62, 0x80
	s_addc_u32 s99, s63, 0
	s_add_i32 s45, s45, s35
	s_mov_b32 m0, s45
	ds_read_b128 v[162:165], v227 offset:49152
	ds_read_b128 v[166:169], v227 offset:50176
	ds_read_b128 v[170:173], v227 offset:51200
	ds_read_b128 v[174:177], v227 offset:52224
	ds_read_b128 v[178:181], v227 offset:53248
	ds_read_b128 v[182:185], v227 offset:54272
	ds_read_b128 v[186:189], v227 offset:55296
	ds_read_b128 v[190:193], v227 offset:56320
	global_load_lds_dwordx4 v0, s[98:99]
	s_add_i32 m0, s45, 0x2000
	s_add_u32 s56, s62, 0x80080
	s_addc_u32 s57, s63, 0
	s_add_i32 s45, s55, s35
	global_load_lds_dwordx4 v208, s[98:99]
	s_mov_b32 m0, s45
	s_nop 0
	global_load_lds_dwordx4 v0, s[56:57]
	s_add_i32 m0, s45, 0x2000
	s_nop 0
	global_load_lds_dwordx4 v208, s[56:57]
	s_mov_b32 m0, s71
	s_nop 0
	global_load_lds_dwordx4 v204, s[100:101]
	s_mov_b32 m0, s74
	s_nop 0
	global_load_lds_dwordx4 v206, s[100:101]
	s_waitcnt vmcnt(8)
	s_waitcnt lgkmcnt(0)
	s_barrier
	s_setprio 1
	s_waitcnt lgkmcnt(0)
	v_mfma_f32_16x16x32_bf16 v[102:105], v[82:85], v[162:165], v[102:105]
	v_mfma_f32_16x16x32_bf16 v[30:33], v[106:109], v[162:165], v[30:33]
	v_mfma_f32_16x16x32_bf16 v[94:97], v[82:85], v[170:173], v[94:97]
	v_mfma_f32_16x16x32_bf16 v[22:25], v[106:109], v[170:173], v[22:25]
	v_mfma_f32_16x16x32_bf16 v[86:89], v[82:85], v[178:181], v[86:89]
	v_mfma_f32_16x16x32_bf16 v[14:17], v[106:109], v[178:181], v[14:17]
	v_mfma_f32_16x16x32_bf16 v[62:65], v[82:85], v[186:189], v[62:65]
	v_mfma_f32_16x16x32_bf16 v[10:13], v[106:109], v[186:189], v[10:13]
	v_mfma_f32_16x16x32_bf16 v[102:105], v[98:101], v[166:169], v[102:105]
	v_mfma_f32_16x16x32_bf16 v[30:33], v[110:113], v[166:169], v[30:33]
	v_mfma_f32_16x16x32_bf16 v[94:97], v[98:101], v[174:177], v[94:97]
	v_mfma_f32_16x16x32_bf16 v[22:25], v[110:113], v[174:177], v[22:25]
	v_mfma_f32_16x16x32_bf16 v[86:89], v[98:101], v[182:185], v[86:89]
	v_mfma_f32_16x16x32_bf16 v[14:17], v[110:113], v[182:185], v[14:17]
	v_mfma_f32_16x16x32_bf16 v[82:85], v[98:101], v[190:193], v[62:65]
	v_mfma_f32_16x16x32_bf16 v[10:13], v[110:113], v[190:193], v[10:13]
	s_setprio 0
	s_setprio 1
	v_mfma_f32_16x16x32_bf16 v[62:65], v[138:141], v[162:165], v[66:69]
	v_mfma_f32_16x16x32_bf16 v[98:101], v[150:153], v[166:169], v[62:65]
	v_mfma_f32_16x16x32_bf16 v[62:65], v[138:141], v[170:173], v[90:93]
	v_mfma_f32_16x16x32_bf16 v[90:93], v[150:153], v[174:177], v[62:65]
	v_mfma_f32_16x16x32_bf16 v[62:65], v[138:141], v[178:181], v[78:81]
	v_mfma_f32_16x16x32_bf16 v[26:29], v[154:157], v[162:165], v[26:29]
	v_mfma_f32_16x16x32_bf16 v[18:21], v[154:157], v[170:173], v[18:21]
	v_mfma_f32_16x16x32_bf16 v[78:81], v[150:153], v[182:185], v[62:65]
	v_mfma_f32_16x16x32_bf16 v[6:9], v[154:157], v[178:181], v[6:9]
	v_mfma_f32_16x16x32_bf16 v[62:65], v[138:141], v[186:189], v[74:77]
	v_mfma_f32_16x16x32_bf16 v[2:5], v[154:157], v[186:189], v[2:5]
	v_mfma_f32_16x16x32_bf16 v[26:29], v[158:161], v[166:169], v[26:29]
	v_mfma_f32_16x16x32_bf16 v[18:21], v[158:161], v[174:177], v[18:21]
	v_mfma_f32_16x16x32_bf16 v[6:9], v[158:161], v[182:185], v[6:9]
	v_mfma_f32_16x16x32_bf16 v[74:77], v[150:153], v[190:193], v[62:65]
	v_mfma_f32_16x16x32_bf16 v[2:5], v[158:161], v[190:193], v[2:5]
	s_setprio 0
	s_barrier
	s_add_i32 s44, s44, 2
	s_add_u32 s41, s41, 0x100
	s_addc_u32 s43, s43, 0
	s_cmp_gt_u32 s44, 29
	s_mov_b64 s[56:57], s[60:61]
	s_cbranch_scc0 .LBB0_1080
	s_branch .Lpeel_exit_4
